# f32 weight reads of the weight-conversion items (read once) use the non-temporal hint, on top of the K/V cache hint
# baseline (speedup 1.0000x reference)
.LBB0_15:
	v_mul_hi_i32 v6, v92, s22
	v_lshrrev_b32_e32 v7, 31, v6
	v_ashrrev_i32_e32 v6, 4, v6
	v_add_u32_e32 v6, v6, v7
	v_mul_lo_u32 v7, v6, s23
	v_sub_u32_e32 v7, v92, v7
	v_lshlrev_b32_e32 v8, 6, v7
	v_lshlrev_b32_e32 v6, 6, v6
	v_or_b32_e32 v78, v6, v41
	v_ashrrev_i32_e32 v9, 31, v8
	v_lshl_add_u64 v[10:11], v[8:9], 2, v[4:5]
	v_or_b32_e32 v9, 2, v78
	v_mad_i64_i32 v[14:15], s[6:7], v9, s24, v[10:11]
	v_or_b32_e32 v9, 4, v78
	v_mad_i64_i32 v[18:19], s[6:7], v9, s24, v[10:11]
	v_or_b32_e32 v9, 6, v78
	v_mad_i64_i32 v[22:23], s[6:7], v9, s24, v[10:11]
	v_or_b32_e32 v9, 8, v78
	v_mad_i64_i32 v[26:27], s[6:7], v9, s24, v[10:11]
	v_or_b32_e32 v9, 10, v78
	v_mad_i64_i32 v[30:31], s[6:7], v9, s24, v[10:11]
	v_or_b32_e32 v9, 12, v78
	v_mad_i64_i32 v[34:35], s[6:7], v9, s24, v[10:11]
	v_or_b32_e32 v9, 14, v78
	v_mad_i64_i32 v[42:43], s[6:7], v9, s24, v[10:11]
	v_or_b32_e32 v9, 16, v78
	v_mad_i64_i32 v[46:47], s[6:7], v9, s24, v[10:11]
	v_or_b32_e32 v9, 18, v78
	v_mad_i64_i32 v[50:51], s[6:7], v9, s24, v[10:11]
	v_or_b32_e32 v9, 20, v78
	v_mad_i64_i32 v[54:55], s[6:7], v9, s24, v[10:11]
	v_or_b32_e32 v9, 22, v78
	v_mad_i64_i32 v[58:59], s[6:7], v9, s24, v[10:11]
	v_or_b32_e32 v9, 24, v78
	v_mad_i64_i32 v[62:63], s[6:7], v9, s24, v[10:11]
	v_or_b32_e32 v9, 26, v78
	v_mad_i64_i32 v[66:67], s[6:7], v9, s24, v[10:11]
	v_or_b32_e32 v9, 28, v78
	v_mad_i64_i32 v[68:69], s[6:7], v9, s24, v[10:11]
	v_or_b32_e32 v9, 30, v78
	v_mad_i64_i32 v[74:75], s[6:7], v9, s24, v[10:11]
	v_or_b32_e32 v9, 32, v78
	v_mad_i64_i32 v[94:95], s[6:7], v9, s24, v[10:11]
	v_or_b32_e32 v9, 34, v78
	v_mad_i64_i32 v[96:97], s[6:7], v9, s24, v[10:11]
	v_or_b32_e32 v9, 36, v78
	v_mad_i64_i32 v[98:99], s[6:7], v9, s24, v[10:11]
	v_or_b32_e32 v9, 38, v78
	v_mad_i64_i32 v[100:101], s[6:7], v9, s24, v[10:11]
	v_or_b32_e32 v9, 40, v78
	v_mad_i64_i32 v[102:103], s[6:7], v9, s24, v[10:11]
	v_or_b32_e32 v9, 42, v78
	v_mad_i64_i32 v[104:105], s[6:7], v9, s24, v[10:11]
	v_or_b32_e32 v9, 44, v78
	v_mad_i64_i32 v[106:107], s[6:7], v9, s24, v[10:11]
	v_or_b32_e32 v9, 46, v78
	v_mad_i64_i32 v[108:109], s[6:7], v9, s24, v[10:11]
	v_or_b32_e32 v9, 48, v78
	v_mad_i64_i32 v[110:111], s[6:7], v9, s24, v[10:11]
	v_or_b32_e32 v9, 50, v78
	v_mad_i64_i32 v[112:113], s[6:7], v9, s24, v[10:11]
	v_or_b32_e32 v9, 52, v78
	v_mad_i64_i32 v[114:115], s[6:7], v9, s24, v[10:11]
	v_or_b32_e32 v9, 54, v78
	v_mad_i64_i32 v[116:117], s[6:7], v9, s24, v[10:11]
	v_or_b32_e32 v9, 56, v78
	v_mad_i64_i32 v[118:119], s[6:7], v9, s24, v[10:11]
	v_or_b32_e32 v9, 58, v78
	v_mad_i64_i32 v[120:121], s[6:7], v9, s24, v[10:11]
	v_or_b32_e32 v9, 60, v78
	v_mad_i64_i32 v[122:123], s[6:7], v9, s24, v[10:11]
	v_or_b32_e32 v9, 62, v78
	v_mad_i64_i32 v[124:125], s[6:7], v9, s24, v[10:11]
	v_mad_i64_i32 v[10:11], s[6:7], v78, s24, v[10:11]
	global_load_dwordx2 v[72:73], v[10:11], off nt
	global_load_dwordx2 v[70:71], v[14:15], off nt
	global_load_dwordx2 v[64:65], v[18:19], off nt
	global_load_dwordx2 v[60:61], v[22:23], off nt
	global_load_dwordx2 v[56:57], v[26:27], off nt
	global_load_dwordx2 v[52:53], v[30:31], off nt
	global_load_dwordx2 v[48:49], v[34:35], off nt
	global_load_dwordx2 v[44:45], v[42:43], off nt
	global_load_dwordx2 v[36:37], v[46:47], off nt
	global_load_dwordx2 v[32:33], v[50:51], off nt
	global_load_dwordx2 v[28:29], v[54:55], off nt
	global_load_dwordx2 v[24:25], v[58:59], off nt
	global_load_dwordx2 v[20:21], v[62:63], off nt
	global_load_dwordx2 v[16:17], v[66:67], off nt
	global_load_dwordx2 v[12:13], v[68:69], off nt
	global_load_dwordx2 v[76:77], v[74:75], off nt
	s_nop 0
	global_load_dwordx2 v[68:69], v[94:95], off nt
	global_load_dwordx2 v[62:63], v[96:97], off nt
	global_load_dwordx2 v[58:59], v[98:99], off nt
	global_load_dwordx2 v[54:55], v[100:101], off nt
	global_load_dwordx2 v[50:51], v[102:103], off nt
	global_load_dwordx2 v[46:47], v[104:105], off nt
	global_load_dwordx2 v[42:43], v[106:107], off nt
	global_load_dwordx2 v[34:35], v[108:109], off nt
	global_load_dwordx2 v[30:31], v[110:111], off nt
	global_load_dwordx2 v[26:27], v[112:113], off nt
	global_load_dwordx2 v[22:23], v[114:115], off nt
	global_load_dwordx2 v[18:19], v[116:117], off nt
	global_load_dwordx2 v[14:15], v[118:119], off nt
	global_load_dwordx2 v[10:11], v[120:121], off nt
	global_load_dwordx2 v[74:75], v[122:123], off nt
	global_load_dwordx2 v[66:67], v[124:125], off nt
	s_and_b64 vcc, exec, s[2:3]
	s_cbranch_vccnz .LBB0_14
	v_ashrrev_i32_e32 v79, 31, v78
	v_lshl_add_u64 v[78:79], v[78:79], 2, s[4:5]
	global_load_dword v94, v[78:79], off
	global_load_dword v96, v[78:79], off offset:8
	global_load_dword v98, v[78:79], off offset:16
	global_load_dword v100, v[78:79], off offset:24
	global_load_dword v102, v[78:79], off offset:32
	global_load_dword v104, v[78:79], off offset:40
	global_load_dword v106, v[78:79], off offset:48
	global_load_dword v108, v[78:79], off offset:56
	global_load_dword v110, v[78:79], off offset:64
	global_load_dword v112, v[78:79], off offset:72
	global_load_dword v114, v[78:79], off offset:80
	global_load_dword v116, v[78:79], off offset:88
	global_load_dword v118, v[78:79], off offset:96
	global_load_dword v120, v[78:79], off offset:104
	global_load_dword v122, v[78:79], off offset:112
	global_load_dword v124, v[78:79], off offset:120
	global_load_dword v126, v[78:79], off offset:128
	global_load_dword v128, v[78:79], off offset:136
	global_load_dword v130, v[78:79], off offset:144
	global_load_dword v132, v[78:79], off offset:152
	global_load_dword v134, v[78:79], off offset:160
	global_load_dword v136, v[78:79], off offset:168
	global_load_dword v138, v[78:79], off offset:176
	global_load_dword v140, v[78:79], off offset:184
	global_load_dword v142, v[78:79], off offset:192
	global_load_dword v144, v[78:79], off offset:200
	global_load_dword v146, v[78:79], off offset:208
	global_load_dword v148, v[78:79], off offset:216
	global_load_dword v150, v[78:79], off offset:224
	global_load_dword v152, v[78:79], off offset:232
	global_load_dword v154, v[78:79], off offset:240
	global_load_dword v156, v[78:79], off offset:248
	s_waitcnt vmcnt(31)
	v_pk_mul_f32 v[72:73], v[72:73], v[94:95] op_sel_hi:[1,0]
	s_waitcnt vmcnt(30)
	v_pk_mul_f32 v[70:71], v[70:71], v[96:97] op_sel_hi:[1,0]
	s_waitcnt vmcnt(29)
	v_pk_mul_f32 v[64:65], v[64:65], v[98:99] op_sel_hi:[1,0]
	s_waitcnt vmcnt(28)
	v_pk_mul_f32 v[60:61], v[60:61], v[100:101] op_sel_hi:[1,0]
	s_waitcnt vmcnt(27)
	v_pk_mul_f32 v[56:57], v[56:57], v[102:103] op_sel_hi:[1,0]
	s_waitcnt vmcnt(26)
	v_pk_mul_f32 v[52:53], v[52:53], v[104:105] op_sel_hi:[1,0]
	s_waitcnt vmcnt(25)
	v_pk_mul_f32 v[48:49], v[48:49], v[106:107] op_sel_hi:[1,0]
	s_waitcnt vmcnt(24)
	v_pk_mul_f32 v[44:45], v[44:45], v[108:109] op_sel_hi:[1,0]
	s_waitcnt vmcnt(23)
	v_pk_mul_f32 v[36:37], v[36:37], v[110:111] op_sel_hi:[1,0]
	s_waitcnt vmcnt(22)
	v_pk_mul_f32 v[32:33], v[32:33], v[112:113] op_sel_hi:[1,0]
	s_waitcnt vmcnt(21)
	v_pk_mul_f32 v[28:29], v[28:29], v[114:115] op_sel_hi:[1,0]
	s_waitcnt vmcnt(20)
	v_pk_mul_f32 v[24:25], v[24:25], v[116:117] op_sel_hi:[1,0]
	s_waitcnt vmcnt(19)
	v_pk_mul_f32 v[20:21], v[20:21], v[118:119] op_sel_hi:[1,0]
	s_waitcnt vmcnt(18)
	v_pk_mul_f32 v[16:17], v[16:17], v[120:121] op_sel_hi:[1,0]
	s_waitcnt vmcnt(17)
	v_pk_mul_f32 v[12:13], v[12:13], v[122:123] op_sel_hi:[1,0]
	s_waitcnt vmcnt(16)
	v_pk_mul_f32 v[76:77], v[76:77], v[124:125] op_sel_hi:[1,0]
	s_waitcnt vmcnt(15)
	v_pk_mul_f32 v[68:69], v[68:69], v[126:127] op_sel_hi:[1,0]
	s_waitcnt vmcnt(14)
	v_pk_mul_f32 v[62:63], v[62:63], v[128:129] op_sel_hi:[1,0]
	s_waitcnt vmcnt(13)
	v_pk_mul_f32 v[58:59], v[58:59], v[130:131] op_sel_hi:[1,0]
	s_waitcnt vmcnt(12)
	v_pk_mul_f32 v[54:55], v[54:55], v[132:133] op_sel_hi:[1,0]
	s_waitcnt vmcnt(11)
	v_pk_mul_f32 v[50:51], v[50:51], v[134:135] op_sel_hi:[1,0]
	s_waitcnt vmcnt(10)
	v_pk_mul_f32 v[46:47], v[46:47], v[136:137] op_sel_hi:[1,0]
	s_waitcnt vmcnt(9)
	v_pk_mul_f32 v[42:43], v[42:43], v[138:139] op_sel_hi:[1,0]
	s_waitcnt vmcnt(8)
	v_pk_mul_f32 v[34:35], v[34:35], v[140:141] op_sel_hi:[1,0]
	s_waitcnt vmcnt(7)
	v_pk_mul_f32 v[30:31], v[30:31], v[142:143] op_sel_hi:[1,0]
	s_waitcnt vmcnt(6)
	v_pk_mul_f32 v[26:27], v[26:27], v[144:145] op_sel_hi:[1,0]
	s_waitcnt vmcnt(5)
	v_pk_mul_f32 v[22:23], v[22:23], v[146:147] op_sel_hi:[1,0]
	s_waitcnt vmcnt(4)
	v_pk_mul_f32 v[18:19], v[18:19], v[148:149] op_sel_hi:[1,0]
	s_waitcnt vmcnt(3)
	v_pk_mul_f32 v[14:15], v[14:15], v[150:151] op_sel_hi:[1,0]
	s_waitcnt vmcnt(2)
	v_pk_mul_f32 v[10:11], v[10:11], v[152:153] op_sel_hi:[1,0]
	s_waitcnt vmcnt(1)
	v_pk_mul_f32 v[74:75], v[74:75], v[154:155] op_sel_hi:[1,0]
	s_waitcnt vmcnt(0)
	v_pk_mul_f32 v[66:67], v[66:67], v[156:157] op_sel_hi:[1,0]
	s_branch .LBB0_14

.LBB0_819:
	v_lshlrev_b32_e32 v6, 6, v6
	v_or_b32_e32 v72, v6, v75
	v_ashrrev_i32_e32 v73, 31, v72
	v_or_b32_e32 v12, 4, v72
	v_ashrrev_i32_e32 v9, 31, v8
	v_mul_lo_u32 v7, v73, s14
	v_mad_u64_u32 v[12:13], s[18:19], v12, s14, 0
	v_lshl_add_u64 v[64:65], v[8:9], 2, v[2:3]
	v_add_u32_e32 v13, v13, v7
	v_or_b32_e32 v10, 2, v72
	v_lshl_add_u64 v[16:17], v[12:13], 2, v[64:65]
	v_or_b32_e32 v12, 6, v72
	v_mad_u64_u32 v[8:9], s[18:19], v72, s14, 0
	v_mad_u64_u32 v[10:11], s[18:19], v10, s14, 0
	v_mad_u64_u32 v[12:13], s[18:19], v12, s14, 0
	v_or_b32_e32 v20, 12, v72
	v_add_u32_e32 v9, v9, v7
	v_add_u32_e32 v11, v11, v7
	v_add_u32_e32 v13, v13, v7
	v_mad_u64_u32 v[20:21], s[18:19], v20, s14, 0
	v_lshl_add_u64 v[8:9], v[8:9], 2, v[64:65]
	v_lshl_add_u64 v[10:11], v[10:11], 2, v[64:65]
	v_lshl_add_u64 v[18:19], v[12:13], 2, v[64:65]
	v_add_u32_e32 v21, v21, v7
	global_load_dwordx2 v[14:15], v[8:9], off nt
	global_load_dwordx2 v[12:13], v[10:11], off nt
	s_nop 0
	global_load_dwordx2 v[10:11], v[16:17], off nt
	global_load_dwordx2 v[8:9], v[18:19], off nt
	v_or_b32_e32 v16, 8, v72
	v_or_b32_e32 v18, 10, v72
	v_lshl_add_u64 v[24:25], v[20:21], 2, v[64:65]
	v_or_b32_e32 v20, 14, v72
	v_mad_u64_u32 v[16:17], s[18:19], v16, s14, 0
	v_mad_u64_u32 v[18:19], s[18:19], v18, s14, 0
	v_mad_u64_u32 v[20:21], s[18:19], v20, s14, 0
	v_or_b32_e32 v28, 20, v72
	v_add_u32_e32 v17, v17, v7
	v_add_u32_e32 v19, v19, v7
	v_add_u32_e32 v21, v21, v7
	v_mad_u64_u32 v[28:29], s[18:19], v28, s14, 0
	v_lshl_add_u64 v[16:17], v[16:17], 2, v[64:65]
	v_lshl_add_u64 v[18:19], v[18:19], 2, v[64:65]
	v_lshl_add_u64 v[26:27], v[20:21], 2, v[64:65]
	v_add_u32_e32 v29, v29, v7
	global_load_dwordx2 v[22:23], v[16:17], off nt
	global_load_dwordx2 v[20:21], v[18:19], off nt
	s_nop 0
	global_load_dwordx2 v[18:19], v[24:25], off nt
	global_load_dwordx2 v[16:17], v[26:27], off nt
	v_or_b32_e32 v24, 16, v72
	v_or_b32_e32 v26, 18, v72
	v_lshl_add_u64 v[32:33], v[28:29], 2, v[64:65]
	v_or_b32_e32 v28, 22, v72
	v_mad_u64_u32 v[24:25], s[18:19], v24, s14, 0
	v_mad_u64_u32 v[26:27], s[18:19], v26, s14, 0
	v_mad_u64_u32 v[28:29], s[18:19], v28, s14, 0
	v_or_b32_e32 v36, 28, v72
	v_add_u32_e32 v25, v25, v7
	v_add_u32_e32 v27, v27, v7
	v_add_u32_e32 v29, v29, v7
	v_mad_u64_u32 v[36:37], s[18:19], v36, s14, 0
	v_lshl_add_u64 v[24:25], v[24:25], 2, v[64:65]
	v_lshl_add_u64 v[26:27], v[26:27], 2, v[64:65]
	v_lshl_add_u64 v[34:35], v[28:29], 2, v[64:65]
	v_add_u32_e32 v37, v37, v7
	global_load_dwordx2 v[30:31], v[24:25], off nt
	global_load_dwordx2 v[28:29], v[26:27], off nt
	s_nop 0
	global_load_dwordx2 v[26:27], v[32:33], off nt
	global_load_dwordx2 v[24:25], v[34:35], off nt
	v_or_b32_e32 v32, 24, v72
	v_or_b32_e32 v34, 26, v72
	v_lshl_add_u64 v[40:41], v[36:37], 2, v[64:65]
	v_or_b32_e32 v36, 30, v72
	v_mad_u64_u32 v[32:33], s[18:19], v32, s14, 0
	v_mad_u64_u32 v[34:35], s[18:19], v34, s14, 0
	v_mad_u64_u32 v[36:37], s[18:19], v36, s14, 0
	v_or_b32_e32 v44, 36, v72
	v_add_u32_e32 v33, v33, v7
	v_add_u32_e32 v35, v35, v7
	v_add_u32_e32 v37, v37, v7
	v_mad_u64_u32 v[44:45], s[18:19], v44, s14, 0
	v_lshl_add_u64 v[32:33], v[32:33], 2, v[64:65]
	v_lshl_add_u64 v[34:35], v[34:35], 2, v[64:65]
	v_lshl_add_u64 v[42:43], v[36:37], 2, v[64:65]
	v_add_u32_e32 v45, v45, v7
	global_load_dwordx2 v[38:39], v[32:33], off nt
	global_load_dwordx2 v[36:37], v[34:35], off nt
	s_nop 0
	global_load_dwordx2 v[34:35], v[40:41], off nt
	global_load_dwordx2 v[32:33], v[42:43], off nt
	v_or_b32_e32 v40, 32, v72
	v_or_b32_e32 v42, 34, v72
	v_lshl_add_u64 v[48:49], v[44:45], 2, v[64:65]
	v_or_b32_e32 v44, 38, v72
	v_mad_u64_u32 v[40:41], s[18:19], v40, s14, 0
	v_mad_u64_u32 v[42:43], s[18:19], v42, s14, 0
	v_mad_u64_u32 v[44:45], s[18:19], v44, s14, 0
	v_or_b32_e32 v52, 44, v72
	v_add_u32_e32 v41, v41, v7
	v_add_u32_e32 v43, v43, v7
	v_add_u32_e32 v45, v45, v7
	v_mad_u64_u32 v[52:53], s[18:19], v52, s14, 0
	v_lshl_add_u64 v[40:41], v[40:41], 2, v[64:65]
	v_lshl_add_u64 v[42:43], v[42:43], 2, v[64:65]
	v_lshl_add_u64 v[50:51], v[44:45], 2, v[64:65]
	v_add_u32_e32 v53, v53, v7
	global_load_dwordx2 v[46:47], v[40:41], off nt
	global_load_dwordx2 v[44:45], v[42:43], off nt
	s_nop 0
	global_load_dwordx2 v[42:43], v[48:49], off nt
	global_load_dwordx2 v[40:41], v[50:51], off nt
	v_or_b32_e32 v48, 40, v72
	v_or_b32_e32 v50, 42, v72
	v_lshl_add_u64 v[56:57], v[52:53], 2, v[64:65]
	v_or_b32_e32 v52, 46, v72
	v_mad_u64_u32 v[48:49], s[18:19], v48, s14, 0
	v_mad_u64_u32 v[50:51], s[18:19], v50, s14, 0
	v_mad_u64_u32 v[52:53], s[18:19], v52, s14, 0
	v_or_b32_e32 v60, 52, v72
	v_add_u32_e32 v49, v49, v7
	v_add_u32_e32 v51, v51, v7
	v_add_u32_e32 v53, v53, v7
	v_mad_u64_u32 v[60:61], s[18:19], v60, s14, 0
	v_lshl_add_u64 v[48:49], v[48:49], 2, v[64:65]
	v_lshl_add_u64 v[50:51], v[50:51], 2, v[64:65]
	v_lshl_add_u64 v[58:59], v[52:53], 2, v[64:65]
	v_add_u32_e32 v61, v61, v7
	global_load_dwordx2 v[54:55], v[48:49], off nt
	global_load_dwordx2 v[52:53], v[50:51], off nt
	s_nop 0
	global_load_dwordx2 v[50:51], v[56:57], off nt
	global_load_dwordx2 v[48:49], v[58:59], off nt
	v_or_b32_e32 v56, 48, v72
	v_or_b32_e32 v58, 50, v72
	v_lshl_add_u64 v[66:67], v[60:61], 2, v[64:65]
	v_or_b32_e32 v60, 54, v72
	v_mad_u64_u32 v[56:57], s[18:19], v56, s14, 0
	v_mad_u64_u32 v[58:59], s[18:19], v58, s14, 0
	v_mad_u64_u32 v[60:61], s[18:19], v60, s14, 0
	v_or_b32_e32 v70, 60, v72
	v_add_u32_e32 v57, v57, v7
	v_add_u32_e32 v59, v59, v7
	v_add_u32_e32 v61, v61, v7
	v_mad_u64_u32 v[70:71], s[18:19], v70, s14, 0
	v_lshl_add_u64 v[56:57], v[56:57], 2, v[64:65]
	v_lshl_add_u64 v[58:59], v[58:59], 2, v[64:65]
	v_lshl_add_u64 v[68:69], v[60:61], 2, v[64:65]
	v_add_u32_e32 v71, v71, v7
	global_load_dwordx2 v[62:63], v[56:57], off nt
	global_load_dwordx2 v[60:61], v[58:59], off nt
	s_nop 0
	global_load_dwordx2 v[58:59], v[66:67], off nt
	global_load_dwordx2 v[56:57], v[68:69], off nt
	v_or_b32_e32 v66, 56, v72
	v_or_b32_e32 v68, 58, v72
	v_lshl_add_u64 v[90:91], v[70:71], 2, v[64:65]
	v_or_b32_e32 v70, 62, v72
	v_mad_u64_u32 v[66:67], s[18:19], v66, s14, 0
	v_mad_u64_u32 v[68:69], s[18:19], v68, s14, 0
	v_mad_u64_u32 v[70:71], s[18:19], v70, s14, 0
	v_add_u32_e32 v67, v67, v7
	v_add_u32_e32 v69, v69, v7
	v_add_u32_e32 v71, v71, v7
	v_lshl_add_u64 v[66:67], v[66:67], 2, v[64:65]
	v_lshl_add_u64 v[68:69], v[68:69], 2, v[64:65]
	v_lshl_add_u64 v[64:65], v[70:71], 2, v[64:65]
	global_load_dwordx2 v[70:71], v[66:67], off nt
	s_nop 0
	global_load_dwordx2 v[68:69], v[68:69], off nt
	s_nop 0
	global_load_dwordx2 v[66:67], v[90:91], off nt
	s_nop 0
	global_load_dwordx2 v[64:65], v[64:65], off nt
	s_andn2_b64 vcc, exec, s[16:17]
	s_cbranch_vccnz .LBB0_816
	v_lshl_add_u64 v[72:73], v[72:73], 2, s[4:5]
	global_load_dword v128, v[72:73], off
	global_load_dword v129, v[72:73], off offset:8
	global_load_dword v130, v[72:73], off offset:16
	global_load_dword v131, v[72:73], off offset:24
	global_load_dword v132, v[72:73], off offset:32
	global_load_dword v133, v[72:73], off offset:40
	global_load_dword v134, v[72:73], off offset:48
	global_load_dword v135, v[72:73], off offset:56
	global_load_dword v136, v[72:73], off offset:64
	global_load_dword v137, v[72:73], off offset:72
	global_load_dword v138, v[72:73], off offset:80
	global_load_dword v139, v[72:73], off offset:88
	global_load_dword v140, v[72:73], off offset:96
	global_load_dword v141, v[72:73], off offset:104
	global_load_dword v142, v[72:73], off offset:112
	global_load_dword v143, v[72:73], off offset:120
	global_load_dword v144, v[72:73], off offset:128
	global_load_dword v145, v[72:73], off offset:136
	global_load_dword v146, v[72:73], off offset:144
	global_load_dword v147, v[72:73], off offset:152
	global_load_dword v148, v[72:73], off offset:160
	global_load_dword v149, v[72:73], off offset:168
	global_load_dword v150, v[72:73], off offset:176
	global_load_dword v151, v[72:73], off offset:184
	global_load_dword v152, v[72:73], off offset:192
	global_load_dword v153, v[72:73], off offset:200
	global_load_dword v154, v[72:73], off offset:208
	global_load_dword v155, v[72:73], off offset:216
	global_load_dword v170, v[72:73], off offset:224
	global_load_dword v171, v[72:73], off offset:232
	global_load_dword v172, v[72:73], off offset:240
	global_load_dword v173, v[72:73], off offset:248
	s_waitcnt vmcnt(0)
	v_pk_mul_f32 v[14:15], v[14:15], v[128:129] op_sel_hi:[1,0]
	v_pk_mul_f32 v[12:13], v[12:13], v[128:129] op_sel:[0,1] op_sel_hi:[1,1]
	v_pk_mul_f32 v[10:11], v[10:11], v[130:131] op_sel_hi:[1,0]
	v_pk_mul_f32 v[8:9], v[8:9], v[130:131] op_sel:[0,1] op_sel_hi:[1,1]
	v_pk_mul_f32 v[22:23], v[22:23], v[132:133] op_sel_hi:[1,0]
	v_pk_mul_f32 v[20:21], v[20:21], v[132:133] op_sel:[0,1] op_sel_hi:[1,1]
	v_pk_mul_f32 v[18:19], v[18:19], v[134:135] op_sel_hi:[1,0]
	v_pk_mul_f32 v[16:17], v[16:17], v[134:135] op_sel:[0,1] op_sel_hi:[1,1]
	v_pk_mul_f32 v[30:31], v[30:31], v[136:137] op_sel_hi:[1,0]
	v_pk_mul_f32 v[28:29], v[28:29], v[136:137] op_sel:[0,1] op_sel_hi:[1,1]
	v_pk_mul_f32 v[26:27], v[26:27], v[138:139] op_sel_hi:[1,0]
	v_pk_mul_f32 v[24:25], v[24:25], v[138:139] op_sel:[0,1] op_sel_hi:[1,1]
	v_pk_mul_f32 v[38:39], v[38:39], v[140:141] op_sel_hi:[1,0]
	v_pk_mul_f32 v[36:37], v[36:37], v[140:141] op_sel:[0,1] op_sel_hi:[1,1]
	v_pk_mul_f32 v[34:35], v[34:35], v[142:143] op_sel_hi:[1,0]
	v_pk_mul_f32 v[32:33], v[32:33], v[142:143] op_sel:[0,1] op_sel_hi:[1,1]
	v_pk_mul_f32 v[46:47], v[46:47], v[144:145] op_sel_hi:[1,0]
	v_pk_mul_f32 v[44:45], v[44:45], v[144:145] op_sel:[0,1] op_sel_hi:[1,1]
	v_pk_mul_f32 v[42:43], v[42:43], v[146:147] op_sel_hi:[1,0]
	v_pk_mul_f32 v[40:41], v[40:41], v[146:147] op_sel:[0,1] op_sel_hi:[1,1]
	v_pk_mul_f32 v[54:55], v[54:55], v[148:149] op_sel_hi:[1,0]
	v_pk_mul_f32 v[52:53], v[52:53], v[148:149] op_sel:[0,1] op_sel_hi:[1,1]
	v_pk_mul_f32 v[50:51], v[50:51], v[150:151] op_sel_hi:[1,0]
	v_pk_mul_f32 v[48:49], v[48:49], v[150:151] op_sel:[0,1] op_sel_hi:[1,1]
	v_pk_mul_f32 v[62:63], v[62:63], v[152:153] op_sel_hi:[1,0]
	v_pk_mul_f32 v[60:61], v[60:61], v[152:153] op_sel:[0,1] op_sel_hi:[1,1]
	v_pk_mul_f32 v[58:59], v[58:59], v[154:155] op_sel_hi:[1,0]
	v_pk_mul_f32 v[56:57], v[56:57], v[154:155] op_sel:[0,1] op_sel_hi:[1,1]
	v_pk_mul_f32 v[70:71], v[70:71], v[170:171] op_sel_hi:[1,0]
	v_pk_mul_f32 v[68:69], v[68:69], v[170:171] op_sel:[0,1] op_sel_hi:[1,1]
	v_pk_mul_f32 v[66:67], v[66:67], v[172:173] op_sel_hi:[1,0]
	v_pk_mul_f32 v[64:65], v[64:65], v[172:173] op_sel:[0,1] op_sel_hi:[1,1]
	s_branch .LBB0_816
